# speedup vs baseline: 1.0039x; 1.0039x over previous
.LBB0_714:
	s_or_b64 exec, exec, s[6:7]
	s_waitcnt lgkmcnt(0)
	s_barrier
	s_and_saveexec_b64 s[0:1], vcc
	s_cbranch_execz .LBB0_716
	v_and_b32_e32 v0, 0x1ffff80, v146
	v_lshlrev_b32_e32 v0, 7, v0
	v_lshl_or_b32 v0, v97, 9, v0
	v_lshl_or_b32 v4, v173, 2, v0
	v_add_u32_e32 v2, 0x400, v4
	ds_read2_b32 v[72:73], v4 offset1:32
	ds_read2_b32 v[0:1], v4 offset0:64 offset1:96
	ds_read2_b32 v[74:75], v2 offset1:32
	ds_read2_b32 v[76:77], v2 offset0:64 offset1:96
	v_add_u32_e32 v2, 0x800, v4
	ds_read2_b32 v[78:79], v2 offset1:32
	ds_read2_b32 v[80:81], v2 offset0:64 offset1:96
	v_add_u32_e32 v2, 0xc00, v4
	ds_read2_b32 v[82:83], v2 offset1:32
	ds_read2_b32 v[84:85], v2 offset0:64 offset1:96
	v_add_u32_e32 v2, 0x1000, v4
	ds_read2_b32 v[86:87], v2 offset1:32
	ds_read2_b32 v[88:89], v2 offset0:64 offset1:96
	v_add_u32_e32 v2, 0x1400, v4
	ds_read2_b32 v[90:91], v2 offset1:32
	ds_read2_b32 v[92:93], v2 offset0:64 offset1:96
	v_add_u32_e32 v2, 0x1800, v4
	ds_read2_b32 v[94:95], v2 offset1:32
	ds_read2_b32 v[98:99], v2 offset0:64 offset1:96
	v_add_u32_e32 v2, 0x1c00, v4
	ds_read2_b32 v[100:101], v2 offset1:32
	ds_read2_b32 v[102:103], v2 offset0:64 offset1:96
	v_add_u32_e32 v2, 0x2000, v4
	ds_read2_b32 v[104:105], v2 offset1:32
	ds_read2_b32 v[106:107], v2 offset0:64 offset1:96
	v_add_u32_e32 v2, 0x2400, v4
	ds_read2_b32 v[108:109], v2 offset1:32
	ds_read2_b32 v[110:111], v2 offset0:64 offset1:96
	v_add_u32_e32 v2, 0x2800, v4
	ds_read2_b32 v[112:113], v2 offset1:32
	s_waitcnt vmcnt(7)
	ds_read2_b32 v[114:115], v2 offset0:64 offset1:96
	v_add_u32_e32 v2, 0x2c00, v4
	ds_read2_b32 v[116:117], v2 offset1:32
	s_waitcnt vmcnt(6)
	ds_read2_b32 v[118:119], v2 offset0:64 offset1:96
	v_add_u32_e32 v2, 0x3000, v4
	v_readlane_b32 s6, v250, 3
	ds_read2_b32 v[120:121], v2 offset1:32
	s_waitcnt vmcnt(5)
	ds_read2_b32 v[122:123], v2 offset0:64 offset1:96
	v_add_u32_e32 v2, 0x3400, v4
	v_add_u32_e32 v5, 0x3c00, v4
	v_readlane_b32 s7, v250, 4
	ds_read2_b32 v[124:125], v2 offset1:32
	s_waitcnt vmcnt(4)
	ds_read2_b32 v[126:127], v2 offset0:64 offset1:96
	ds_read2_b32 v[2:3], v5 offset1:32
	s_and_b64 s[6:7], s[6:7], exec
	v_readlane_b32 s16, v252, 7
	s_cselect_b32 s6, 0x200, 0
	v_readlane_b32 s30, v252, 21
	v_readlane_b32 s31, v252, 22
	s_add_u32 s6, s30, s6
	s_waitcnt lgkmcnt(14)
	v_pk_fma_f32 v[72:73], v[150:151], v[72:73], v[64:65] op_sel_hi:[0,1,1] neg_lo:[1,0,0] neg_hi:[1,0,0]
	s_addc_u32 s7, s31, 0
	v_add_u32_e32 v4, 0x3800, v4
	v_pk_fma_f32 v[66:67], v[150:151], v[0:1], v[66:67] op_sel_hi:[0,1,1] neg_lo:[1,0,0] neg_hi:[1,0,0]
	s_waitcnt vmcnt(2)
	v_pk_mul_f32 v[134:135], v[72:73], v[72:73]
	ds_read2_b32 v[6:7], v5 offset0:64 offset1:96
	ds_read2_b32 v[128:129], v4 offset1:32
	ds_read2_b32 v[130:131], v4 offset0:64 offset1:96
	s_waitcnt lgkmcnt(3)
	v_pk_fma_f32 v[4:5], v[150:151], v[2:3], v[70:71] op_sel_hi:[0,1,1] neg_lo:[1,0,0] neg_hi:[1,0,0]
	v_pk_mul_f32 v[132:133], v[66:67], v[66:67]
	global_load_dwordx4 v[0:3], v148, s[6:7]
	global_load_dwordx4 v[230:233], v148, s[6:7] offset:32
	global_load_dwordx4 v[234:237], v148, s[6:7] offset:64
	global_load_dwordx4 v[238:241], v148, s[6:7] offset:96
	global_load_dwordx4 v[242:245], v148, s[6:7] offset:128
	global_load_dwordx4 v[246:249], v148, s[6:7] offset:160
	v_pk_fma_f32 v[14:15], v[150:151], v[126:127], v[14:15] op_sel_hi:[0,1,1] neg_lo:[1,0,0] neg_hi:[1,0,0]
	v_add_f32_e32 v126, v134, v135
	v_pk_fma_f32 v[74:75], v[150:151], v[74:75], v[52:53] op_sel_hi:[0,1,1] neg_lo:[1,0,0] neg_hi:[1,0,0]
	v_add_f32_e32 v126, v126, v132
	v_pk_mul_f32 v[136:137], v[74:75], v[74:75]
	v_add_f32_e32 v126, v126, v133
	v_pk_fma_f32 v[64:65], v[150:151], v[76:77], v[54:55] op_sel_hi:[0,1,1] neg_lo:[1,0,0] neg_hi:[1,0,0]
	v_add_f32_e32 v126, v126, v136
	v_pk_mul_f32 v[76:77], v[64:65], v[64:65]
	v_add_f32_e32 v126, v126, v137
	v_pk_fma_f32 v[78:79], v[150:151], v[78:79], v[56:57] op_sel_hi:[0,1,1] neg_lo:[1,0,0] neg_hi:[1,0,0]
	v_add_f32_e32 v76, v126, v76
	s_waitcnt vmcnt(7)
	v_pk_mul_f32 v[138:139], v[78:79], v[78:79]
	v_add_f32_e32 v76, v76, v77
	v_pk_fma_f32 v[58:59], v[150:151], v[80:81], v[58:59] op_sel_hi:[0,1,1] neg_lo:[1,0,0] neg_hi:[1,0,0]
	v_add_f32_e32 v76, v76, v138
	v_pk_mul_f32 v[80:81], v[58:59], v[58:59]
	v_add_f32_e32 v76, v76, v139
	v_pk_fma_f32 v[82:83], v[150:151], v[82:83], v[60:61] op_sel_hi:[0,1,1] neg_lo:[1,0,0] neg_hi:[1,0,0]
	v_add_f32_e32 v76, v76, v80
	v_pk_fma_f32 v[52:53], v[150:151], v[84:85], v[62:63] op_sel_hi:[0,1,1] neg_lo:[1,0,0] neg_hi:[1,0,0]
	v_pk_mul_f32 v[84:85], v[82:83], v[82:83]
	v_add_f32_e32 v76, v76, v81
	v_add_f32_e32 v76, v76, v84
	v_pk_mul_f32 v[62:63], v[52:53], v[52:53]
	v_add_f32_e32 v76, v76, v85
	v_pk_fma_f32 v[60:61], v[150:151], v[86:87], v[48:49] op_sel_hi:[0,1,1] neg_lo:[1,0,0] neg_hi:[1,0,0]
	v_add_f32_e32 v62, v76, v62
	v_pk_mul_f32 v[86:87], v[60:61], v[60:61]
	v_add_f32_e32 v62, v62, v63
	v_pk_fma_f32 v[50:51], v[150:151], v[88:89], v[50:51] op_sel_hi:[0,1,1] neg_lo:[1,0,0] neg_hi:[1,0,0]
	v_add_f32_e32 v62, v62, v86
	v_pk_mul_f32 v[88:89], v[50:51], v[50:51]
	v_add_f32_e32 v62, v62, v87
	v_pk_fma_f32 v[56:57], v[150:151], v[90:91], v[36:37] op_sel_hi:[0,1,1] neg_lo:[1,0,0] neg_hi:[1,0,0]
	v_add_f32_e32 v62, v62, v88
	v_pk_mul_f32 v[90:91], v[56:57], v[56:57]
	v_add_f32_e32 v62, v62, v89
	v_pk_fma_f32 v[48:49], v[150:151], v[92:93], v[38:39] op_sel_hi:[0,1,1] neg_lo:[1,0,0] neg_hi:[1,0,0]
	v_add_f32_e32 v62, v62, v90
	v_pk_mul_f32 v[92:93], v[48:49], v[48:49]
	v_add_f32_e32 v62, v62, v91
	v_pk_fma_f32 v[54:55], v[150:151], v[94:95], v[40:41] op_sel_hi:[0,1,1] neg_lo:[1,0,0] neg_hi:[1,0,0]
	v_add_f32_e32 v62, v62, v92
	v_pk_mul_f32 v[94:95], v[54:55], v[54:55]
	v_add_f32_e32 v62, v62, v93
	v_pk_fma_f32 v[38:39], v[150:151], v[98:99], v[42:43] op_sel_hi:[0,1,1] neg_lo:[1,0,0] neg_hi:[1,0,0]
	v_add_f32_e32 v62, v62, v94
	v_pk_mul_f32 v[98:99], v[38:39], v[38:39]
	v_add_f32_e32 v62, v62, v95
	v_pk_fma_f32 v[44:45], v[150:151], v[100:101], v[44:45] op_sel_hi:[0,1,1] neg_lo:[1,0,0] neg_hi:[1,0,0]
	v_add_f32_e32 v62, v62, v98
	v_pk_mul_f32 v[100:101], v[44:45], v[44:45]
	v_add_f32_e32 v62, v62, v99
	v_pk_fma_f32 v[36:37], v[150:151], v[102:103], v[46:47] op_sel_hi:[0,1,1] neg_lo:[1,0,0] neg_hi:[1,0,0]
	v_add_f32_e32 v62, v62, v100
	v_pk_mul_f32 v[46:47], v[36:37], v[36:37]
	v_add_f32_e32 v62, v62, v101
	v_pk_fma_f32 v[42:43], v[150:151], v[104:105], v[32:33] op_sel_hi:[0,1,1] neg_lo:[1,0,0] neg_hi:[1,0,0]
	v_add_f32_e32 v46, v62, v46
	v_pk_mul_f32 v[104:105], v[42:43], v[42:43]
	v_add_f32_e32 v46, v46, v47
	v_pk_fma_f32 v[34:35], v[150:151], v[106:107], v[34:35] op_sel_hi:[0,1,1] neg_lo:[1,0,0] neg_hi:[1,0,0]
	v_add_f32_e32 v46, v46, v104
	v_pk_mul_f32 v[102:103], v[34:35], v[34:35]
	v_add_f32_e32 v46, v46, v105
	v_pk_fma_f32 v[40:41], v[150:151], v[108:109], v[20:21] op_sel_hi:[0,1,1] neg_lo:[1,0,0] neg_hi:[1,0,0]
	v_add_f32_e32 v46, v46, v102
	v_pk_mul_f32 v[108:109], v[40:41], v[40:41]
	v_add_f32_e32 v46, v46, v103
	v_pk_fma_f32 v[32:33], v[150:151], v[110:111], v[22:23] op_sel_hi:[0,1,1] neg_lo:[1,0,0] neg_hi:[1,0,0]
	v_add_f32_e32 v46, v46, v108
	v_pk_mul_f32 v[106:107], v[32:33], v[32:33]
	v_add_f32_e32 v46, v46, v109
	v_pk_fma_f32 v[22:23], v[150:151], v[114:115], v[26:27] op_sel_hi:[0,1,1] neg_lo:[1,0,0] neg_hi:[1,0,0]
	v_pk_fma_f32 v[26:27], v[150:151], v[112:113], v[24:25] op_sel_hi:[0,1,1] neg_lo:[1,0,0] neg_hi:[1,0,0]
	v_add_f32_e32 v46, v46, v106
	v_pk_mul_f32 v[112:113], v[26:27], v[26:27]
	v_add_f32_e32 v46, v46, v107
	v_add_f32_e32 v46, v46, v112
	v_pk_mul_f32 v[110:111], v[22:23], v[22:23]
	v_add_f32_e32 v46, v46, v113
	v_pk_fma_f32 v[24:25], v[150:151], v[116:117], v[28:29] op_sel_hi:[0,1,1] neg_lo:[1,0,0] neg_hi:[1,0,0]
	v_add_f32_e32 v46, v46, v110
	v_pk_mul_f32 v[28:29], v[24:25], v[24:25]
	v_add_f32_e32 v46, v46, v111
	v_pk_fma_f32 v[20:21], v[150:151], v[118:119], v[30:31] op_sel_hi:[0,1,1] neg_lo:[1,0,0] neg_hi:[1,0,0]
	v_add_f32_e32 v28, v46, v28
	v_pk_mul_f32 v[30:31], v[20:21], v[20:21]
	v_add_f32_e32 v28, v28, v29
	v_pk_fma_f32 v[16:17], v[150:151], v[120:121], v[16:17] op_sel_hi:[0,1,1] neg_lo:[1,0,0] neg_hi:[1,0,0]
	v_add_f32_e32 v28, v28, v30
	v_pk_mul_f32 v[116:117], v[16:17], v[16:17]
	v_add_f32_e32 v28, v28, v31
	v_pk_fma_f32 v[18:19], v[150:151], v[122:123], v[18:19] op_sel_hi:[0,1,1] neg_lo:[1,0,0] neg_hi:[1,0,0]
	v_add_f32_e32 v28, v28, v116
	v_pk_mul_f32 v[114:115], v[18:19], v[18:19]
	v_add_f32_e32 v28, v28, v117
	v_pk_fma_f32 v[12:13], v[150:151], v[124:125], v[12:13] op_sel_hi:[0,1,1] neg_lo:[1,0,0] neg_hi:[1,0,0]
	v_add_f32_e32 v28, v28, v114
	v_pk_mul_f32 v[120:121], v[12:13], v[12:13]
	v_add_f32_e32 v28, v28, v115
	v_add_f32_e32 v28, v28, v120
	v_pk_mul_f32 v[118:119], v[14:15], v[14:15]
	v_add_f32_e32 v28, v28, v121
	s_waitcnt lgkmcnt(1)
	v_pk_fma_f32 v[8:9], v[150:151], v[128:129], v[8:9] op_sel_hi:[0,1,1] neg_lo:[1,0,0] neg_hi:[1,0,0]
	v_add_f32_e32 v28, v28, v118
	v_pk_mul_f32 v[124:125], v[8:9], v[8:9]
	v_add_f32_e32 v28, v28, v119
	s_waitcnt lgkmcnt(0)
	v_pk_fma_f32 v[10:11], v[150:151], v[130:131], v[10:11] op_sel_hi:[0,1,1] neg_lo:[1,0,0] neg_hi:[1,0,0]
	v_add_f32_e32 v28, v28, v124
	v_pk_mul_f32 v[122:123], v[10:11], v[10:11]
	v_add_f32_e32 v28, v28, v125
	v_add_f32_e32 v28, v28, v122
	v_pk_mul_f32 v[70:71], v[4:5], v[4:5]
	v_add_f32_e32 v28, v28, v123
	v_pk_fma_f32 v[6:7], v[150:151], v[6:7], v[68:69] op_sel_hi:[0,1,1] neg_lo:[1,0,0] neg_hi:[1,0,0]
	v_add_f32_e32 v28, v28, v70
	v_pk_mul_f32 v[68:69], v[6:7], v[6:7]
	v_add_f32_e32 v28, v28, v71
	v_add_f32_e32 v28, v28, v68
	v_add_f32_e32 v30, v28, v69
	ds_bpermute_b32 v31, v147, v30
	v_readlane_b32 s8, v253, 53
	v_readlane_b32 s9, v253, 54
	v_sub_f32_e32 v46, 1.0, v151
	v_readlane_b32 s17, v252, 8
	s_waitcnt lgkmcnt(0)
	v_add_f32_e32 v30, v30, v31
	v_fmamk_f32 v30, v30, 0x3c000000, v211
	v_mul_f32_e32 v31, 0x4b800000, v30
	v_cmp_gt_f32_e32 vcc, s33, v30
	v_lshl_add_u64 v[28:29], s[8:9], 0, v[152:153]
	v_lshl_add_u64 v[28:29], s[4:5], 1, v[28:29]
	v_cndmask_b32_e32 v30, v30, v31, vcc
	v_rsq_f32_e32 v47, v30
	v_lshlrev_b32_e32 v30, 3, v97
	v_mov_b32_e32 v31, v96
	v_lshl_add_u64 v[28:29], v[28:29], 0, v[30:31]
	v_mul_f32_e32 v30, 0x45800000, v47
	v_cndmask_b32_e32 v30, v47, v30, vcc
	v_mul_f32_e32 v30, v46, v30
	v_pk_mul_f32 v[46:47], v[72:73], v[30:31] op_sel_hi:[1,0]
	v_pk_mul_f32 v[58:59], v[58:59], v[30:31] op_sel_hi:[1,0]
	s_waitcnt vmcnt(5)
	v_pk_mul_f32 v[0:1], v[0:1], v[46:47]
	v_pk_mul_f32 v[46:47], v[66:67], v[30:31] op_sel_hi:[1,0]
	v_cvt_pk_bf16_f32 v0, v0, v1
	v_pk_mul_f32 v[2:3], v[2:3], v[46:47]
	v_pk_mul_f32 v[46:47], v[74:75], v[30:31] op_sel_hi:[1,0]
	v_cvt_pk_bf16_f32 v1, v2, v3
	global_store_dwordx2 v[28:29], v[0:1], off
	v_pk_mul_f32 v[52:53], v[52:53], v[30:31] op_sel_hi:[1,0]
	v_pk_mul_f32 v[50:51], v[50:51], v[30:31] op_sel_hi:[1,0]
	v_pk_mul_f32 v[48:49], v[48:49], v[30:31] op_sel_hi:[1,0]
	v_pk_mul_f32 v[38:39], v[38:39], v[30:31] op_sel_hi:[1,0]
	v_pk_mul_f32 v[36:37], v[36:37], v[30:31] op_sel_hi:[1,0]
	v_pk_mul_f32 v[34:35], v[34:35], v[30:31] op_sel_hi:[1,0]
	v_pk_mul_f32 v[32:33], v[32:33], v[30:31] op_sel_hi:[1,0]
	v_pk_mul_f32 v[26:27], v[26:27], v[30:31] op_sel_hi:[1,0]
	v_pk_mul_f32 v[22:23], v[22:23], v[30:31] op_sel_hi:[1,0]
	v_pk_mul_f32 v[20:21], v[20:21], v[30:31] op_sel_hi:[1,0]
	v_pk_mul_f32 v[16:17], v[16:17], v[30:31] op_sel_hi:[1,0]
	v_pk_mul_f32 v[18:19], v[18:19], v[30:31] op_sel_hi:[1,0]
	v_pk_mul_f32 v[12:13], v[12:13], v[30:31] op_sel_hi:[1,0]
	v_pk_mul_f32 v[14:15], v[14:15], v[30:31] op_sel_hi:[1,0]
	v_pk_mul_f32 v[8:9], v[8:9], v[30:31] op_sel_hi:[1,0]
	v_pk_mul_f32 v[10:11], v[10:11], v[30:31] op_sel_hi:[1,0]
	v_pk_mul_f32 v[4:5], v[4:5], v[30:31] op_sel_hi:[1,0]
	v_pk_mul_f32 v[6:7], v[6:7], v[30:31] op_sel_hi:[1,0]
	v_readlane_b32 s18, v252, 9
	v_readlane_b32 s19, v252, 10
	v_readlane_b32 s20, v252, 11
	v_readlane_b32 s21, v252, 12
	v_readlane_b32 s22, v252, 13
	v_readlane_b32 s23, v252, 14
	v_readlane_b32 s24, v252, 15
	v_readlane_b32 s25, v252, 16
	v_readlane_b32 s26, v252, 17
	v_readlane_b32 s27, v252, 18
	v_readlane_b32 s28, v252, 19
	v_readlane_b32 s29, v252, 20
	s_waitcnt vmcnt(5)
	v_pk_mul_f32 v[0:1], v[230:231], v[46:47]
	v_pk_mul_f32 v[46:47], v[64:65], v[30:31] op_sel_hi:[1,0]
	v_cvt_pk_bf16_f32 v0, v0, v1
	v_pk_mul_f32 v[2:3], v[232:233], v[46:47]
	v_pk_mul_f32 v[46:47], v[78:79], v[30:31] op_sel_hi:[1,0]
	v_cvt_pk_bf16_f32 v1, v2, v3
	global_store_dwordx2 v[28:29], v[0:1], off offset:16
	global_load_dwordx4 v[230:233], v148, s[6:7] offset:192
	s_waitcnt vmcnt(6)
	v_pk_mul_f32 v[0:1], v[234:235], v[46:47]
	v_pk_mul_f32 v[2:3], v[236:237], v[58:59]
	v_cvt_pk_bf16_f32 v0, v0, v1
	v_cvt_pk_bf16_f32 v1, v2, v3
	global_store_dwordx2 v[28:29], v[0:1], off offset:32
	global_load_dwordx4 v[234:237], v148, s[6:7] offset:224
	v_pk_mul_f32 v[46:47], v[82:83], v[30:31] op_sel_hi:[1,0]
	s_waitcnt vmcnt(7)
	v_pk_mul_f32 v[2:3], v[52:53], v[240:241]
	v_pk_mul_f32 v[0:1], v[46:47], v[238:239]
	v_pk_mul_f32 v[46:47], v[60:61], v[30:31] op_sel_hi:[1,0]
	v_cvt_pk_bf16_f32 v0, v0, v1
	v_cvt_pk_bf16_f32 v1, v2, v3
	global_store_dwordx2 v[28:29], v[0:1], off offset:48
	global_load_dwordx4 v[238:241], v148, s[6:7] offset:256
	s_waitcnt vmcnt(8)
	v_pk_mul_f32 v[0:1], v[46:47], v[242:243]
	v_pk_mul_f32 v[2:3], v[50:51], v[244:245]
	v_cvt_pk_bf16_f32 v0, v0, v1
	v_cvt_pk_bf16_f32 v1, v2, v3
	global_store_dwordx2 v[28:29], v[0:1], off offset:64
	global_load_dwordx4 v[242:245], v148, s[6:7] offset:288
	v_pk_mul_f32 v[46:47], v[56:57], v[30:31] op_sel_hi:[1,0]
	s_waitcnt vmcnt(9)
	v_pk_mul_f32 v[2:3], v[48:49], v[248:249]
	v_pk_mul_f32 v[0:1], v[46:47], v[246:247]
	v_pk_mul_f32 v[46:47], v[54:55], v[30:31] op_sel_hi:[1,0]
	v_cvt_pk_bf16_f32 v0, v0, v1
	v_cvt_pk_bf16_f32 v1, v2, v3
	global_store_dwordx2 v[28:29], v[0:1], off offset:80
	global_load_dwordx4 v[246:249], v148, s[6:7] offset:320
	s_waitcnt vmcnt(8)
	v_pk_mul_f32 v[0:1], v[46:47], v[230:231]
	v_pk_mul_f32 v[2:3], v[38:39], v[232:233]
	v_cvt_pk_bf16_f32 v0, v0, v1
	v_cvt_pk_bf16_f32 v1, v2, v3
	global_store_dwordx2 v[28:29], v[0:1], off offset:96
	global_load_dwordx4 v[230:233], v148, s[6:7] offset:352
	v_pk_mul_f32 v[38:39], v[44:45], v[30:31] op_sel_hi:[1,0]
	s_waitcnt vmcnt(8)
	v_pk_mul_f32 v[2:3], v[36:37], v[236:237]
	v_pk_mul_f32 v[0:1], v[38:39], v[234:235]
	v_pk_mul_f32 v[36:37], v[42:43], v[30:31] op_sel_hi:[1,0]
	v_cvt_pk_bf16_f32 v0, v0, v1
	v_cvt_pk_bf16_f32 v1, v2, v3
	global_store_dwordx2 v[28:29], v[0:1], off offset:112
	global_load_dwordx4 v[234:237], v148, s[6:7] offset:384
	s_waitcnt vmcnt(8)
	v_pk_mul_f32 v[0:1], v[36:37], v[238:239]
	v_pk_mul_f32 v[2:3], v[34:35], v[240:241]
	v_cvt_pk_bf16_f32 v0, v0, v1
	v_cvt_pk_bf16_f32 v1, v2, v3
	global_store_dwordx2 v[28:29], v[0:1], off offset:128
	global_load_dwordx4 v[238:241], v148, s[6:7] offset:416
	v_pk_mul_f32 v[34:35], v[40:41], v[30:31] op_sel_hi:[1,0]
	s_waitcnt vmcnt(8)
	v_pk_mul_f32 v[2:3], v[32:33], v[244:245]
	v_pk_mul_f32 v[0:1], v[34:35], v[242:243]
	s_nop 0
	v_cvt_pk_bf16_f32 v0, v0, v1
	v_cvt_pk_bf16_f32 v1, v2, v3
	global_store_dwordx2 v[28:29], v[0:1], off offset:144
	global_load_dwordx4 v[242:245], v148, s[6:7] offset:448
	s_waitcnt vmcnt(8)
	v_pk_mul_f32 v[0:1], v[26:27], v[246:247]
	v_pk_mul_f32 v[2:3], v[22:23], v[248:249]
	v_cvt_pk_bf16_f32 v0, v0, v1
	v_cvt_pk_bf16_f32 v1, v2, v3
	global_store_dwordx2 v[28:29], v[0:1], off offset:160
	global_load_dwordx4 v[246:249], v148, s[6:7] offset:480
	v_pk_mul_f32 v[22:23], v[24:25], v[30:31] op_sel_hi:[1,0]
	s_waitcnt vmcnt(8)
	v_pk_mul_f32 v[2:3], v[20:21], v[232:233]
	v_pk_mul_f32 v[0:1], v[22:23], v[230:231]
	s_nop 0
	v_cvt_pk_bf16_f32 v0, v0, v1
	v_cvt_pk_bf16_f32 v1, v2, v3
	global_store_dwordx2 v[28:29], v[0:1], off offset:176
	s_waitcnt vmcnt(7)
	v_pk_mul_f32 v[0:1], v[16:17], v[234:235]
	v_pk_mul_f32 v[2:3], v[18:19], v[236:237]
	v_cvt_pk_bf16_f32 v0, v0, v1
	v_cvt_pk_bf16_f32 v1, v2, v3
	global_store_dwordx2 v[28:29], v[0:1], off offset:192
	s_waitcnt vmcnt(6)
	v_pk_mul_f32 v[0:1], v[12:13], v[238:239]
	v_pk_mul_f32 v[2:3], v[14:15], v[240:241]
	v_cvt_pk_bf16_f32 v0, v0, v1
	v_cvt_pk_bf16_f32 v1, v2, v3
	global_store_dwordx2 v[28:29], v[0:1], off offset:208
	s_waitcnt vmcnt(5)
	v_pk_mul_f32 v[0:1], v[8:9], v[242:243]
	v_pk_mul_f32 v[2:3], v[10:11], v[244:245]
	v_cvt_pk_bf16_f32 v0, v0, v1
	v_cvt_pk_bf16_f32 v1, v2, v3
	global_store_dwordx2 v[28:29], v[0:1], off offset:224
	s_waitcnt vmcnt(4)
	v_pk_mul_f32 v[0:1], v[4:5], v[246:247]
	v_pk_mul_f32 v[2:3], v[6:7], v[248:249]
	v_cvt_pk_bf16_f32 v0, v0, v1
	v_cvt_pk_bf16_f32 v1, v2, v3
	global_store_dwordx2 v[28:29], v[0:1], off offset:240
